# attention loop-edge edits: loop-control SALU moved into the odd step, first PV MFMA of each step ahead of the K fragment reads
# speedup vs baseline: 1.0016x; 1.0016x over previous
; #define LAS __attribute__((address_space(3)))
; __device__ __forceinline__ void attn_unit2(LAS unsigned char* lds, const bf16_t* __restrict__ Q, const bf16_t* __restrict__ KN, const bf16_t* __restrict__ KPE, ...
;     ...
;         SOFTMAX2(sa0, sa1, ma, la, oa0, oa1, pa);
;         SOFTMAX2(sb0, sb1, mb, lb, ob0, ob1, pb);
;     ...
;         const LAS unsigned char* va = lds + sc + va_off;
; #pragma unroll
;         for (int st = 0; st < 4; ++st) {
;             const bf16x8 v0 = *(const LAS bf16x8*)(va + st * 32);
;             const bf16x8 v1 = *(const LAS bf16x8*)(va + 32 * VROW + st * 32);
;             const bf16x8 fa = __builtin_bit_cast(bf16x8, pa[st]), fb = __builtin_bit_cast(bf16x8, pb[st]);
;             oa0 = __builtin_amdgcn_mfma_f32_32x32x16_bf16(v0, fa, oa0, 0, 0, 0);
;             oa1 = __builtin_amdgcn_mfma_f32_32x32x16_bf16(v1, fa, oa1, 0, 0, 0);
;             ob0 = __builtin_amdgcn_mfma_f32_32x32x16_bf16(v0, fb, ob0, 0, 0, 0);
;             ob1 = __builtin_amdgcn_mfma_f32_32x32x16_bf16(v1, fb, ob1, 0, 0, 0);
;         }
.Lat_loop:
	s_waitcnt lgkmcnt(3)
	v_mfma_f32_32x32x16_bf16 v[16:31], v[196:199], v[96:99], v[16:31]
	v_add3_u32 v224, s34, v183, v128
	ds_read_b128 v[212:215], v224 offset:6656
	ds_read_b128 v[216:219], v224 offset:6688
	ds_read_b128 v[220:223], v224 offset:6720
	v_exp_f32_e32 v64, v64
	v_exp_f32_e32 v65, v65
	v_exp_f32_e32 v66, v66
	v_exp_f32_e32 v67, v67
	s_waitcnt lgkmcnt(5)
	v_mfma_f32_32x32x16_bf16 v[48:63], v[200:203], v[96:99], v[48:63]
	v_exp_f32_e32 v68, v68
	v_exp_f32_e32 v69, v69
	v_add_f32_e32 v230, v64, v65
	v_exp_f32_e32 v70, v70
	s_waitcnt lgkmcnt(4)
	v_mfma_f32_32x32x16_bf16 v[16:31], v[204:207], v[100:103], v[16:31]
	v_exp_f32_e32 v71, v71
	v_add_f32_e32 v231, v66, v67
	v_exp_f32_e32 v72, v72
	v_exp_f32_e32 v73, v73
	s_waitcnt lgkmcnt(3)
	v_mfma_f32_32x32x16_bf16 v[48:63], v[208:211], v[100:103], v[48:63]
	v_add_f32_e32 v230, v230, v68
	v_add_f32_e32 v231, v231, v69
	v_exp_f32_e32 v74, v74
	v_exp_f32_e32 v75, v75
	v_add_f32_e32 v230, v230, v70
	v_add_f32_e32 v231, v231, v71
	v_mfma_f32_32x32x16_bf16 v[32:47], v[196:199], v[112:115], v[32:47]
	v_exp_f32_e32 v76, v76
	v_exp_f32_e32 v77, v77
	v_add_f32_e32 v230, v230, v72
	v_add_f32_e32 v231, v231, v73
	v_mfma_f32_32x32x16_bf16 v[0:15], v[200:203], v[112:115], v[0:15]
	v_exp_f32_e32 v78, v78
	v_exp_f32_e32 v79, v79
	v_add_f32_e32 v230, v230, v74
	v_add_f32_e32 v231, v231, v75
	v_mfma_f32_32x32x16_bf16 v[32:47], v[204:207], v[116:119], v[32:47]
	v_add_f32_e32 v230, v230, v76
	v_add_f32_e32 v231, v231, v77
	v_add_f32_e32 v230, v230, v78
	v_add_f32_e32 v231, v231, v79
	v_mfma_f32_32x32x16_bf16 v[0:15], v[208:211], v[116:119], v[0:15]
	v_add_f32_e32 v230, v230, v231
	v_add3_u32 v225, s34, v187, v128
	ds_read_b128 v[196:199], v225 offset:13312
	ds_read_b128 v[200:203], v225 offset:17920
	ds_read_b128 v[204:207], v225 offset:13344
	ds_read_b128 v[208:211], v225 offset:17952
	v_cmp_lt_f32_e32 vcc, 0x45800000, v230
	s_cbranch_vccnz .Lat_resc_aE

; #define LAS __attribute__((address_space(3)))
; __device__ __forceinline__ void attn_unit2(LAS unsigned char* lds, const bf16_t* __restrict__ Q, const bf16_t* __restrict__ KN, const bf16_t* __restrict__ KPE, ...
;     ...
;         SOFTMAX2(sa0, sa1, ma, la, oa0, oa1, pa);
;         SOFTMAX2(sb0, sb1, mb, lb, ob0, ob1, pb);
;     ...
;         const LAS unsigned char* va = lds + sc + va_off;
; #pragma unroll
;         for (int st = 0; st < 4; ++st) {
;             const bf16x8 v0 = *(const LAS bf16x8*)(va + st * 32);
;             const bf16x8 v1 = *(const LAS bf16x8*)(va + 32 * VROW + st * 32);
;             const bf16x8 fa = __builtin_bit_cast(bf16x8, pa[st]), fb = __builtin_bit_cast(bf16x8, pb[st]);
;             oa0 = __builtin_amdgcn_mfma_f32_32x32x16_bf16(v0, fa, oa0, 0, 0, 0);
;             oa1 = __builtin_amdgcn_mfma_f32_32x32x16_bf16(v1, fa, oa1, 0, 0, 0);
;             ob0 = __builtin_amdgcn_mfma_f32_32x32x16_bf16(v0, fb, ob0, 0, 0, 0);
;             ob1 = __builtin_amdgcn_mfma_f32_32x32x16_bf16(v1, fb, ob1, 0, 0, 0);
;         }
;         __builtin_amdgcn_sched_barrier(0);
;         __syncthreads();
.Lat_back_bE:
	v_add_f32_e32 v193, v193, v230
	v_cvt_pk_bf16_f32 v80, v80, v81
	v_cvt_pk_bf16_f32 v81, v82, v83
	v_mfma_f32_32x32x16_bf16 v[112:127], v[220:223], v[174:177], v[112:127]
	v_cvt_pk_bf16_f32 v82, v84, v85
	v_cvt_pk_bf16_f32 v83, v86, v87
	v_cvt_pk_bf16_f32 v84, v88, v89
	v_mfma_f32_32x32x16_bf16 v[112:127], v[240:243], v[248:251], v[112:127]
	v_cvt_pk_bf16_f32 v85, v90, v91
	v_cvt_pk_bf16_f32 v86, v92, v93
	v_cvt_pk_bf16_f32 v87, v94, v95
	s_waitcnt vmcnt(0)
	s_barrier
	s_cmp_lt_u32 s27, 2
	s_cselect_b32 s14, s10, s11
	s_add_i32 s14, s14, s24
	v_mfma_f32_32x32x16_bf16 v[16:31], v[196:199], v[64:67], v[16:31]
	v_add3_u32 v224, s26, v183, v128
	ds_read_b128 v[212:215], v224 offset:0
	ds_read_b128 v[216:219], v224 offset:32
	ds_read_b128 v[220:223], v224 offset:64
	v_exp_f32_e32 v96, v96
	v_exp_f32_e32 v97, v97
	s_cmpk_gt_u32 s27, 0x81
	s_cbranch_scc1 .Lat_dmaL_0
	s_and_b64 vcc, exec, s[4:5]
	s_cbranch_vccnz .Lat_dmaL_0
	v_mad_u64_u32 v[234:235], s[16:17], v182, s14, v[180:181]
	s_add_i32 m0, s25, s19
	s_nop 0
	global_load_lds_dwordx4 v[234:235], off

; #define LAS __attribute__((address_space(3)))
; #define DMAT(kt, so) do { const unsigned rb_ = (unsigned)ROWBASE(kt); _Pragma("unroll") for (int r = 0; r < 3; ++r) if (wid + 8 * r < 22) \
;         __builtin_amdgcn_global_load_lds((const unsigned*)(dsrc[r] + (size_t)rb_ * dmul[r]), (LAS unsigned*)(lds + (so) + dlds[r]), 16, 0, 0); } while (0)
; __device__ __forceinline__ void attn_unit2(LAS unsigned char* lds, const bf16_t* __restrict__ Q, const bf16_t* __restrict__ KN, const bf16_t* __restrict__ KPE, ...
;     ...
;         for (int ds = 0; ds < 6; ++ds) {
;             const bf16x8 k0 = *(const LAS bf16x8*)(ka + ds * 32);
;             const bf16x8 k1 = *(const LAS bf16x8*)(ka + 32 * KROW + ds * 32);
;             sa0 = __builtin_amdgcn_mfma_f32_32x32x16_bf16(k0, qa[ds], sa0, 0, 0, 0);
;             sa1 = __builtin_amdgcn_mfma_f32_32x32x16_bf16(k1, qa[ds], sa1, 0, 0, 0);
;             sb0 = __builtin_amdgcn_mfma_f32_32x32x16_bf16(k0, qb[ds], sb0, 0, 0, 0);
;             sb1 = __builtin_amdgcn_mfma_f32_32x32x16_bf16(k1, qb[ds], sb1, 0, 0, 0);
;         }
;         __builtin_amdgcn_sched_barrier(0);
;         if (t + 2 < ntiles) DMAT(t + 2, snn);
;         u32x4 pa[4], pb[4];
;     ...
;         SOFTMAX2(sa0, sa1, ma, la, oa0, oa1, pa);
;         SOFTMAX2(sb0, sb1, mb, lb, ob0, ob1, pb);
;     ...
;         { const int tmp = sc; sc = sn; sn = snn; snn = tmp; }
.Lat_back_aO:
	v_add_f32_e32 v191, v191, v230
	v_cvt_pk_bf16_f32 v96, v96, v97
	v_mfma_f32_32x32x16_bf16 v[64:79], v[240:243], v[244:247], 0
	v_cvt_pk_bf16_f32 v97, v98, v99
	v_cvt_pk_bf16_f32 v98, v100, v101
	v_cvt_pk_bf16_f32 v99, v102, v103
	s_waitcnt lgkmcnt(6)
	v_mfma_f32_32x32x16_bf16 v[64:79], v[212:215], v[130:133], v[64:79]
	v_cvt_pk_bf16_f32 v100, v104, v105
	v_cvt_pk_bf16_f32 v101, v106, v107
	v_cvt_pk_bf16_f32 v102, v108, v109
	v_cvt_pk_bf16_f32 v103, v110, v111
	v_mfma_f32_32x32x16_bf16 v[80:95], v[212:215], v[138:141], 0
	ds_read_b128 v[212:215], v224 offset:96
	v_exp_f32_e32 v112, v112
	v_exp_f32_e32 v113, v113
	v_exp_f32_e32 v114, v114
	s_waitcnt lgkmcnt(6)
	v_mfma_f32_32x32x16_bf16 v[64:79], v[216:219], v[134:137], v[64:79]
	v_exp_f32_e32 v115, v115
	s_add_i32 s27, s27, 1
	s_add_i32 s24, s24, 64
	s_mov_b32 s14, s34
	s_mov_b32 s34, s26
	s_mov_b32 s26, s25
	s_mov_b32 s25, s14
	v_exp_f32_e32 v116, v116
	v_exp_f32_e32 v117, v117
	v_add_f32_e32 v230, v112, v113
	v_mfma_f32_32x32x16_bf16 v[80:95], v[216:219], v[142:145], v[80:95]
	ds_read_b128 v[216:219], v224 offset:128
	v_exp_f32_e32 v118, v118
	v_exp_f32_e32 v119, v119
	v_add_f32_e32 v231, v114, v115
	s_waitcnt lgkmcnt(6)
	v_mfma_f32_32x32x16_bf16 v[64:79], v[220:223], v[146:149], v[64:79]
	v_exp_f32_e32 v120, v120
	v_exp_f32_e32 v121, v121
	v_add_f32_e32 v230, v230, v116
	v_add_f32_e32 v231, v231, v117
	v_mfma_f32_32x32x16_bf16 v[80:95], v[220:223], v[154:157], v[80:95]
	ds_read_b128 v[220:223], v224 offset:160
	v_exp_f32_e32 v122, v122
	v_exp_f32_e32 v123, v123
	v_add_f32_e32 v230, v230, v118
	s_waitcnt lgkmcnt(2)
	v_mfma_f32_32x32x16_bf16 v[64:79], v[212:215], v[150:153], v[64:79]
	v_add_f32_e32 v231, v231, v119
	v_exp_f32_e32 v124, v124
	v_exp_f32_e32 v125, v125
	v_add_f32_e32 v230, v230, v120
	v_mfma_f32_32x32x16_bf16 v[80:95], v[212:215], v[158:161], v[80:95]
	v_add_f32_e32 v231, v231, v121
	v_exp_f32_e32 v126, v126
	v_exp_f32_e32 v127, v127
	s_waitcnt lgkmcnt(1)
	v_mfma_f32_32x32x16_bf16 v[64:79], v[216:219], v[162:165], v[64:79]
	v_add_f32_e32 v230, v230, v122
	v_add_f32_e32 v231, v231, v123
	v_add_f32_e32 v230, v230, v124
	v_add_f32_e32 v231, v231, v125
	v_mfma_f32_32x32x16_bf16 v[80:95], v[216:219], v[170:173], v[80:95]
	v_add_f32_e32 v230, v230, v126
	v_add_f32_e32 v231, v231, v127
	v_add_f32_e32 v230, v230, v231
	s_waitcnt lgkmcnt(0)
	v_mfma_f32_32x32x16_bf16 v[64:79], v[220:223], v[166:169], v[64:79]
	v_cmp_lt_f32_e32 vcc, 0x45800000, v230
	s_cbranch_vccnz .Lat_resc_bO
.Lat_back_bO:
	v_add_f32_e32 v193, v193, v230
	v_cvt_pk_bf16_f32 v112, v112, v113
	v_cvt_pk_bf16_f32 v113, v114, v115
	v_mfma_f32_32x32x16_bf16 v[80:95], v[220:223], v[174:177], v[80:95]
	v_cvt_pk_bf16_f32 v114, v116, v117
	v_cvt_pk_bf16_f32 v115, v118, v119
	v_cvt_pk_bf16_f32 v116, v120, v121
	v_mfma_f32_32x32x16_bf16 v[80:95], v[240:243], v[248:251], v[80:95]
	v_cvt_pk_bf16_f32 v117, v122, v123
	v_cvt_pk_bf16_f32 v118, v124, v125
	v_cvt_pk_bf16_f32 v119, v126, v127
	s_cmpk_lg_i32 s27, 0x84
	s_cbranch_scc1 .Lat_loop
	s_waitcnt lgkmcnt(3)
	v_mfma_f32_32x32x16_bf16 v[16:31], v[196:199], v[96:99], v[16:31]
	s_waitcnt lgkmcnt(2)
	v_mfma_f32_32x32x16_bf16 v[48:63], v[200:203], v[96:99], v[48:63]
	s_waitcnt lgkmcnt(1)
	v_mfma_f32_32x32x16_bf16 v[16:31], v[204:207], v[100:103], v[16:31]
	s_waitcnt lgkmcnt(0)
	v_mfma_f32_32x32x16_bf16 v[48:63], v[208:211], v[100:103], v[48:63]
	v_mfma_f32_32x32x16_bf16 v[32:47], v[196:199], v[112:115], v[32:47]
	v_mfma_f32_32x32x16_bf16 v[0:15], v[200:203], v[112:115], v[0:15]
	v_mfma_f32_32x32x16_bf16 v[32:47], v[204:207], v[116:119], v[32:47]
	v_mfma_f32_32x32x16_bf16 v[0:15], v[208:211], v[116:119], v[0:15]
	s_branch .Lat_done
